# MLA sunk barrier + first four V^T LDS reads moved one exp group later (larger pre-barrier window)
# speedup vs baseline: 1.0275x; 1.0028x over previous
.LBB0_546:
	s_or_b64 exec, exec, s[24:25]
	global_load_dwordx4 v[206:209], v[252:253], off
	s_mov_b64 s[0:1], 0x10000
	v_lshl_add_u64 v[250:251], v[250:251], 0, s[0:1]
	v_lshl_add_u64 v[252:253], v[252:253], 0, s[0:1]
	v_exp_f32_e32 v0, v82
	v_exp_f32_e32 v34, v83
	v_mfma_f32_32x32x16_bf16 v[114:129], v[98:101], v[150:153], v[66:81]
	v_exp_f32_e32 v36, v85
	v_add_f32_e32 v35, v34, v0
	v_cvt_pk_bf16_f32 v34, v0, v34
	v_exp_f32_e32 v0, v84
	s_nop 0
	v_add_f32_e32 v35, v0, v35
	v_add_f32_e32 v37, v36, v35
	v_cvt_pk_bf16_f32 v35, v0, v36
	v_exp_f32_e32 v0, v86
	v_mfma_f32_32x32x16_bf16 v[98:113], v[202:205], v[150:153], v[66:81]
	v_exp_f32_e32 v36, v87
	v_exp_f32_e32 v38, v88
	v_exp_f32_e32 v39, v89
	v_add_f32_e32 v37, v0, v37
	v_add_f32_e32 v37, v36, v37
	v_cvt_pk_bf16_f32 v36, v0, v36
	v_add_f32_e32 v0, v38, v37
	v_add_f32_e32 v0, v39, v0
	v_cvt_pk_bf16_f32 v37, v38, v39
	v_exp_f32_e32 v38, v90
	v_exp_f32_e32 v39, v91
	v_mfma_f32_32x32x16_bf16 v[114:129], v[198:201], v[146:149], v[114:129]
	v_exp_f32_e32 v40, v93
	v_add_f32_e32 v0, v38, v0
	v_add_f32_e32 v0, v39, v0
	v_cvt_pk_bf16_f32 v38, v38, v39
	v_exp_f32_e32 v39, v92
	s_nop 0
	v_add_f32_e32 v0, v39, v0
	v_add_f32_e32 v0, v40, v0
	v_cvt_pk_bf16_f32 v39, v39, v40
	v_exp_f32_e32 v40, v94
	v_exp_f32_e32 v41, v95
	v_mfma_f32_32x32x16_bf16 v[98:113], v[194:197], v[146:149], v[98:113]
	v_exp_f32_e32 v42, v97
	v_add_f32_e32 v0, v40, v0
	v_add_f32_e32 v0, v41, v0
	v_cvt_pk_bf16_f32 v40, v40, v41
	v_exp_f32_e32 v41, v96
	s_nop 0
	v_add_f32_e32 v0, v41, v0
	v_add_f32_e32 v0, v42, v0
	v_cvt_pk_bf16_f32 v41, v41, v42
	v_mfma_f32_32x32x16_bf16 v[114:129], v[190:193], v[142:145], v[114:129]
	v_exp_f32_e32 v42, v50
	v_exp_f32_e32 v43, v51
	v_add_f32_e32 v0, v42, v0
	v_add_f32_e32 v0, v43, v0
	v_cvt_pk_bf16_f32 v42, v42, v43
	v_mfma_f32_32x32x16_bf16 v[98:113], v[186:189], v[142:145], v[98:113]
	v_exp_f32_e32 v43, v52
	v_exp_f32_e32 v44, v53
	s_waitcnt lgkmcnt(0)
	s_barrier
	ds_read_b64_tr_b16 v[82:83], v231 offset:26624
	ds_read_b64_tr_b16 v[84:85], v231 offset:27392
	ds_read_b64_tr_b16 v[46:47], v231 offset:26688
	ds_read_b64_tr_b16 v[48:49], v231 offset:27456
	ds_read_b64_tr_b16 v[86:87], v231 offset:29696
	ds_read_b64_tr_b16 v[88:89], v231 offset:30464
	v_add_f32_e32 v0, v43, v0
	v_add_f32_e32 v0, v44, v0
	v_cvt_pk_bf16_f32 v43, v43, v44
	v_mfma_f32_32x32x16_bf16 v[114:129], v[182:185], v[138:141], v[114:129]
	v_exp_f32_e32 v44, v54
	v_exp_f32_e32 v45, v55
	ds_read_b64_tr_b16 v[90:91], v231 offset:29760
	ds_read_b64_tr_b16 v[92:93], v231 offset:30528
	v_add_f32_e32 v0, v44, v0
	v_add_f32_e32 v0, v45, v0
	v_cvt_pk_bf16_f32 v44, v44, v45
	v_mfma_f32_32x32x16_bf16 v[98:113], v[178:181], v[138:141], v[98:113]
	v_exp_f32_e32 v45, v56
	v_exp_f32_e32 v50, v57
	ds_read_b64_tr_b16 v[94:95], v231 offset:32768
	ds_read_b64_tr_b16 v[96:97], v231 offset:33536
	v_add_f32_e32 v0, v45, v0
	v_add_f32_e32 v0, v50, v0
	v_cvt_pk_bf16_f32 v45, v45, v50
	v_mfma_f32_32x32x16_bf16 v[114:129], v[174:177], v[134:137], v[114:129]
	v_exp_f32_e32 v50, v58
	v_exp_f32_e32 v51, v59
	ds_read_b64_tr_b16 v[210:211], v231 offset:32832
	ds_read_b64_tr_b16 v[212:213], v231 offset:33600
	v_add_f32_e32 v0, v50, v0
	v_add_f32_e32 v0, v51, v0
	v_cvt_pk_bf16_f32 v54, v50, v51
	v_mfma_f32_32x32x16_bf16 v[98:113], v[170:173], v[134:137], v[98:113]
	v_exp_f32_e32 v50, v60
	v_exp_f32_e32 v51, v61
	ds_read_b64_tr_b16 v[58:59], v231 offset:35840
	ds_read_b64_tr_b16 v[60:61], v231 offset:36608
	v_add_f32_e32 v0, v50, v0
	v_add_f32_e32 v0, v51, v0
	v_cvt_pk_bf16_f32 v55, v50, v51
	v_mfma_f32_32x32x16_bf16 v[114:129], v[166:169], v[130:133], v[114:129]
	v_exp_f32_e32 v50, v62
	v_exp_f32_e32 v51, v63
	ds_read_b64_tr_b16 v[214:215], v231 offset:35904
	ds_read_b64_tr_b16 v[216:217], v231 offset:36672
	v_add_f32_e32 v0, v50, v0
	v_add_f32_e32 v0, v51, v0
	v_cvt_pk_bf16_f32 v56, v50, v51
	v_mfma_f32_32x32x16_bf16 v[98:113], v[158:161], v[130:133], v[98:113]
	v_exp_f32_e32 v50, v64
	v_exp_f32_e32 v51, v65
	v_add_f32_e32 v0, v50, v0
	v_add_f32_e32 v62, v51, v0
	v_cvt_pk_bf16_f32 v57, v50, v51
	s_waitcnt lgkmcnt(14)
	v_mfma_f32_32x32x16_bf16 v[18:33], v[82:85], v[34:37], v[18:33]
	ds_read_b128 v[50:53], v233
	ds_read_b128 v[198:201], v233 offset:6656
	v_add_f32_e32 v0, v242, v62
	s_waitcnt lgkmcnt(14)
	v_mfma_f32_32x32x16_bf16 v[2:17], v[46:49], v[34:37], v[2:17]
	ds_read_b128 v[202:205], v233 offset:32
	ds_read_b128 v[194:197], v233 offset:6688
	s_waitcnt lgkmcnt(14)
	v_mfma_f32_32x32x16_bf16 v[18:33], v[86:89], v[38:41], v[18:33]
	ds_read_b128 v[190:193], v233 offset:64
	ds_read_b128 v[186:189], v233 offset:6720
	s_waitcnt lgkmcnt(14)
	v_mfma_f32_32x32x16_bf16 v[2:17], v[90:93], v[38:41], v[2:17]
	ds_read_b128 v[182:185], v233 offset:96
	ds_read_b128 v[178:181], v233 offset:6752
	s_waitcnt lgkmcnt(14)
	v_mfma_f32_32x32x16_bf16 v[18:33], v[94:97], v[42:45], v[18:33]
	ds_read_b128 v[174:177], v233 offset:128
	ds_read_b128 v[170:173], v233 offset:6784
	s_waitcnt lgkmcnt(14)
	v_mfma_f32_32x32x16_bf16 v[2:17], v[210:213], v[42:45], v[2:17]
	ds_read_b128 v[166:169], v233 offset:160
	ds_read_b128 v[158:161], v233 offset:6816
	s_waitcnt lgkmcnt(14)
	v_mfma_f32_32x32x16_bf16 v[18:33], v[58:61], v[54:57], v[18:33]
	s_waitcnt lgkmcnt(12)
	v_mfma_f32_32x32x16_bf16 v[2:17], v[214:217], v[54:57], v[2:17]
	v_mov_b32_e32 v34, v62
	s_nop 1
	v_permlane32_swap_b32_e32 v62, v34
	v_max_f32_e32 v34, v62, v34
	v_cmp_lt_f32_e32 vcc, s74, v34
	s_cbranch_vccz .LBB0_558
	v_frexp_exp_i32_f32_e32 v34, v34
	v_cvt_f32_i32_e32 v34, v34
	v_cndmask_b32_e32 v35, 0, v34, vcc
	v_exp_f32_e64 v36, -v35
	v_add_f32_e32 v235, v235, v35
	v_xor_b32_e32 v34, 0x80000000, v235
	v_sub_f32_e32 v129, v129, v35
	v_pk_mul_f32 v[32:33], v[32:33], v[36:37] op_sel_hi:[1,0]
	v_pk_mul_f32 v[30:31], v[30:31], v[36:37] op_sel_hi:[1,0]
	v_pk_mul_f32 v[28:29], v[28:29], v[36:37] op_sel_hi:[1,0]
	v_pk_mul_f32 v[26:27], v[26:27], v[36:37] op_sel_hi:[1,0]
	v_pk_mul_f32 v[24:25], v[24:25], v[36:37] op_sel_hi:[1,0]
	v_pk_mul_f32 v[22:23], v[22:23], v[36:37] op_sel_hi:[1,0]
	v_pk_mul_f32 v[20:21], v[20:21], v[36:37] op_sel_hi:[1,0]
	v_pk_mul_f32 v[18:19], v[18:19], v[36:37] op_sel_hi:[1,0]
	v_pk_mul_f32 v[16:17], v[16:17], v[36:37] op_sel_hi:[1,0]
	v_pk_mul_f32 v[14:15], v[14:15], v[36:37] op_sel_hi:[1,0]
	v_pk_mul_f32 v[12:13], v[12:13], v[36:37] op_sel_hi:[1,0]
	v_pk_mul_f32 v[10:11], v[10:11], v[36:37] op_sel_hi:[1,0]
	v_pk_mul_f32 v[8:9], v[8:9], v[36:37] op_sel_hi:[1,0]
	v_pk_mul_f32 v[6:7], v[6:7], v[36:37] op_sel_hi:[1,0]
	v_pk_mul_f32 v[4:5], v[4:5], v[36:37] op_sel_hi:[1,0]
	v_pk_mul_f32 v[2:3], v[2:3], v[36:37] op_sel_hi:[1,0]
	v_sub_f32_e32 v128, v128, v35
	v_sub_f32_e32 v127, v127, v35
	v_sub_f32_e32 v126, v126, v35
	v_sub_f32_e32 v125, v125, v35
	v_sub_f32_e32 v124, v124, v35
	v_sub_f32_e32 v123, v123, v35
	v_sub_f32_e32 v122, v122, v35
	v_sub_f32_e32 v121, v121, v35
	v_sub_f32_e32 v120, v120, v35
	v_sub_f32_e32 v119, v119, v35
	v_sub_f32_e32 v118, v118, v35
	v_sub_f32_e32 v117, v117, v35
	v_sub_f32_e32 v116, v116, v35
	v_sub_f32_e32 v115, v115, v35
	v_sub_f32_e32 v114, v114, v35
	v_sub_f32_e32 v113, v113, v35
	v_sub_f32_e32 v112, v112, v35
	v_sub_f32_e32 v111, v111, v35
	v_sub_f32_e32 v110, v110, v35
	v_sub_f32_e32 v109, v109, v35
	v_sub_f32_e32 v108, v108, v35
	v_sub_f32_e32 v107, v107, v35
	v_sub_f32_e32 v106, v106, v35
	v_sub_f32_e32 v105, v105, v35
	v_sub_f32_e32 v104, v104, v35
	v_sub_f32_e32 v103, v103, v35
	v_sub_f32_e32 v102, v102, v35
	v_sub_f32_e32 v101, v101, v35
	v_sub_f32_e32 v100, v100, v35
	v_sub_f32_e32 v99, v99, v35
	v_sub_f32_e32 v98, v98, v35
	v_mul_f32_e32 v0, v0, v36
	v_mov_b32_e32 v35, v34
	v_mov_b32_e32 v36, v34
	v_mov_b32_e32 v37, v34
	v_mov_b32_e32 v38, v34
	v_mov_b32_e32 v39, v34
	v_mov_b32_e32 v40, v34
	v_mov_b32_e32 v41, v34
	v_mov_b32_e32 v42, v34
	v_mov_b32_e32 v43, v34
	v_mov_b32_e32 v44, v34
	v_mov_b32_e32 v45, v34
	v_mov_b32_e32 v46, v34
	v_mov_b32_e32 v47, v34
	v_mov_b32_e32 v48, v34
	v_mov_b32_e32 v49, v34
	v_mov_b32_e32 v66, v34
	v_mov_b32_e32 v67, v34
	v_mov_b32_e32 v68, v34
	v_mov_b32_e32 v69, v34
	v_mov_b32_e32 v70, v34
	v_mov_b32_e32 v71, v34
	v_mov_b32_e32 v72, v34
	v_mov_b32_e32 v73, v34
	v_mov_b32_e32 v74, v34
	v_mov_b32_e32 v75, v34
	v_mov_b32_e32 v76, v34
	v_mov_b32_e32 v77, v34
	v_mov_b32_e32 v78, v34
	v_mov_b32_e32 v79, v34
	v_mov_b32_e32 v80, v34
	v_mov_b32_e32 v81, v34
	s_waitcnt vmcnt(1)
	ds_write_b128 v232, v[162:165] offset:13312
	s_and_saveexec_b64 s[24:25], s[4:5]

.LBB0_553:
	global_load_dwordx4 v[206:209], v[252:253], off
	s_mov_b64 s[0:1], 0x10000
	v_lshl_add_u64 v[250:251], v[250:251], 0, s[0:1]
	v_lshl_add_u64 v[252:253], v[252:253], 0, s[0:1]
	v_mfma_f32_32x32x16_bf16 v[82:97], v[50:53], v[150:153], v[66:81]
	v_exp_f32_e32 v50, v114
	v_exp_f32_e32 v51, v115
	v_add_f32_e32 v52, 0, v50
	v_cvt_pk_bf16_f32 v114, v50, v51
	v_exp_f32_e32 v50, v116
	v_add_f32_e32 v52, v51, v52
	v_exp_f32_e32 v51, v117
	v_add_f32_e32 v52, v50, v52
	v_add_f32_e32 v52, v51, v52
	v_cvt_pk_bf16_f32 v115, v50, v51
	v_exp_f32_e32 v116, v118
	v_exp_f32_e32 v117, v119
	v_exp_f32_e32 v118, v120
	v_exp_f32_e32 v119, v121
	v_add_f32_e32 v50, v116, v52
	v_add_f32_e32 v120, v117, v50
	v_mfma_f32_32x32x16_bf16 v[50:65], v[198:201], v[150:153], v[66:81]
	v_cvt_pk_bf16_f32 v116, v116, v117
	v_add_f32_e32 v117, v118, v120
	v_add_f32_e32 v120, v119, v117
	v_cvt_pk_bf16_f32 v117, v118, v119
	v_exp_f32_e32 v118, v122
	v_exp_f32_e32 v119, v123
	v_mfma_f32_32x32x16_bf16 v[82:97], v[202:205], v[146:149], v[82:97]
	v_exp_f32_e32 v121, v125
	v_add_f32_e32 v120, v118, v120
	v_add_f32_e32 v120, v119, v120
	v_cvt_pk_bf16_f32 v118, v118, v119
	v_exp_f32_e32 v119, v124
	s_nop 0
	v_add_f32_e32 v120, v119, v120
	v_add_f32_e32 v120, v121, v120
	v_cvt_pk_bf16_f32 v119, v119, v121
	v_exp_f32_e32 v121, v126
	v_exp_f32_e32 v122, v127
	v_mfma_f32_32x32x16_bf16 v[50:65], v[194:197], v[146:149], v[50:65]
	v_add_f32_e32 v120, v121, v120
	v_add_f32_e32 v123, v122, v120
	v_cvt_pk_bf16_f32 v120, v121, v122
	v_exp_f32_e32 v121, v128
	v_exp_f32_e32 v122, v129
	v_add_f32_e32 v123, v121, v123
	v_add_f32_e32 v123, v122, v123
	v_cvt_pk_bf16_f32 v121, v121, v122
	v_mfma_f32_32x32x16_bf16 v[82:97], v[190:193], v[142:145], v[82:97]
	v_exp_f32_e32 v98, v98
	v_exp_f32_e32 v99, v99
	v_add_f32_e32 v122, v98, v123
	v_add_f32_e32 v123, v99, v122
	v_cvt_pk_bf16_f32 v122, v98, v99
	v_mfma_f32_32x32x16_bf16 v[50:65], v[186:189], v[142:145], v[50:65]
	v_exp_f32_e32 v98, v100
	v_exp_f32_e32 v99, v101
	s_waitcnt lgkmcnt(0)
	s_barrier
	ds_read_b64_tr_b16 v[190:191], v231 offset:38912
	ds_read_b64_tr_b16 v[192:193], v231 offset:39680
	ds_read_b64_tr_b16 v[126:127], v231 offset:38976
	ds_read_b64_tr_b16 v[128:129], v231 offset:39744
	ds_read_b64_tr_b16 v[186:187], v231 offset:41984
	ds_read_b64_tr_b16 v[188:189], v231 offset:42752
	v_add_f32_e32 v100, v98, v123
	v_add_f32_e32 v100, v99, v100
	v_cvt_pk_bf16_f32 v123, v98, v99
	v_mfma_f32_32x32x16_bf16 v[82:97], v[182:185], v[138:141], v[82:97]
	v_exp_f32_e32 v98, v102
	v_exp_f32_e32 v99, v103
	ds_read_b64_tr_b16 v[182:183], v231 offset:42048
	ds_read_b64_tr_b16 v[184:185], v231 offset:42816
	v_add_f32_e32 v100, v98, v100
	v_add_f32_e32 v100, v99, v100
	v_cvt_pk_bf16_f32 v124, v98, v99
	v_mfma_f32_32x32x16_bf16 v[50:65], v[178:181], v[138:141], v[50:65]
	v_exp_f32_e32 v98, v104
	v_exp_f32_e32 v99, v105
	ds_read_b64_tr_b16 v[210:211], v231 offset:45056
	ds_read_b64_tr_b16 v[212:213], v231 offset:45824
	v_add_f32_e32 v100, v98, v100
	v_add_f32_e32 v100, v99, v100
	v_cvt_pk_bf16_f32 v125, v98, v99
	v_mfma_f32_32x32x16_bf16 v[82:97], v[174:177], v[134:137], v[82:97]
	v_exp_f32_e32 v98, v106
	v_exp_f32_e32 v99, v107
	ds_read_b64_tr_b16 v[214:215], v231 offset:45120
	ds_read_b64_tr_b16 v[216:217], v231 offset:45888
	v_add_f32_e32 v100, v98, v100
	v_add_f32_e32 v100, v99, v100
	v_cvt_pk_bf16_f32 v102, v98, v99
	v_mfma_f32_32x32x16_bf16 v[50:65], v[170:173], v[134:137], v[50:65]
	v_exp_f32_e32 v98, v108
	v_exp_f32_e32 v99, v109
	ds_read_b64_tr_b16 v[106:107], v231 offset:48128
	ds_read_b64_tr_b16 v[108:109], v231 offset:48896
	v_add_f32_e32 v100, v98, v100
	v_add_f32_e32 v100, v99, v100
	v_cvt_pk_bf16_f32 v103, v98, v99
	v_mfma_f32_32x32x16_bf16 v[82:97], v[166:169], v[130:133], v[82:97]
	v_exp_f32_e32 v98, v110
	v_exp_f32_e32 v99, v111
	ds_read_b64_tr_b16 v[244:245], v231 offset:48192
	ds_read_b64_tr_b16 v[246:247], v231 offset:48960
	v_add_f32_e32 v100, v98, v100
	v_add_f32_e32 v100, v99, v100
	v_cvt_pk_bf16_f32 v104, v98, v99
	v_mfma_f32_32x32x16_bf16 v[50:65], v[158:161], v[130:133], v[50:65]
	v_exp_f32_e32 v98, v112
	v_exp_f32_e32 v99, v113
	v_add_f32_e32 v100, v98, v100
	v_add_f32_e32 v110, v99, v100
	v_cvt_pk_bf16_f32 v105, v98, v99
	s_waitcnt lgkmcnt(14)
	v_mfma_f32_32x32x16_bf16 v[18:33], v[190:193], v[114:117], v[18:33]
	ds_read_b128 v[98:101], v233 offset:13312
	ds_read_b128 v[202:205], v233 offset:19968
	v_add_f32_e32 v242, v0, v110
	s_waitcnt lgkmcnt(14)
	v_mfma_f32_32x32x16_bf16 v[2:17], v[126:129], v[114:117], v[2:17]
	ds_read_b128 v[198:201], v233 offset:13344
	ds_read_b128 v[194:197], v233 offset:20000
	s_waitcnt lgkmcnt(14)
	v_mfma_f32_32x32x16_bf16 v[18:33], v[186:189], v[118:121], v[18:33]
	ds_read_b128 v[190:193], v233 offset:13376
	ds_read_b128 v[186:189], v233 offset:20032
	s_waitcnt lgkmcnt(14)
	v_mfma_f32_32x32x16_bf16 v[2:17], v[182:185], v[118:121], v[2:17]
	ds_read_b128 v[182:185], v233 offset:13408
	ds_read_b128 v[178:181], v233 offset:20064
	s_waitcnt lgkmcnt(14)
	v_mfma_f32_32x32x16_bf16 v[18:33], v[210:213], v[122:125], v[18:33]
	ds_read_b128 v[174:177], v233 offset:13440
	ds_read_b128 v[170:173], v233 offset:20096
	s_waitcnt lgkmcnt(14)
	v_mfma_f32_32x32x16_bf16 v[2:17], v[214:217], v[122:125], v[2:17]
	ds_read_b128 v[166:169], v233 offset:13472
	ds_read_b128 v[158:161], v233 offset:20128
	s_waitcnt lgkmcnt(14)
	v_mfma_f32_32x32x16_bf16 v[18:33], v[106:109], v[102:105], v[18:33]
	s_waitcnt lgkmcnt(12)
	v_mfma_f32_32x32x16_bf16 v[2:17], v[244:247], v[102:105], v[2:17]
	v_mov_b32_e32 v0, v110
	s_nop 1
	v_permlane32_swap_b32_e32 v110, v0
	v_max_f32_e32 v0, v110, v0
	v_cmp_lt_f32_e32 vcc, s74, v0
	s_cbranch_vccz .LBB0_555
	v_frexp_exp_i32_f32_e32 v0, v0
	v_cvt_f32_i32_e32 v0, v0
	v_cndmask_b32_e32 v35, 0, v0, vcc
	v_exp_f32_e64 v0, -v35
	v_add_f32_e32 v235, v235, v35
	v_xor_b32_e32 v34, 0x80000000, v235
	v_sub_f32_e32 v97, v97, v35
	v_pk_mul_f32 v[32:33], v[32:33], v[0:1] op_sel_hi:[1,0]
	v_pk_mul_f32 v[30:31], v[30:31], v[0:1] op_sel_hi:[1,0]
	v_pk_mul_f32 v[28:29], v[28:29], v[0:1] op_sel_hi:[1,0]
	v_pk_mul_f32 v[26:27], v[26:27], v[0:1] op_sel_hi:[1,0]
	v_pk_mul_f32 v[24:25], v[24:25], v[0:1] op_sel_hi:[1,0]
	v_pk_mul_f32 v[22:23], v[22:23], v[0:1] op_sel_hi:[1,0]
	v_pk_mul_f32 v[20:21], v[20:21], v[0:1] op_sel_hi:[1,0]
	v_pk_mul_f32 v[18:19], v[18:19], v[0:1] op_sel_hi:[1,0]
	v_pk_mul_f32 v[16:17], v[16:17], v[0:1] op_sel_hi:[1,0]
	v_pk_mul_f32 v[14:15], v[14:15], v[0:1] op_sel_hi:[1,0]
	v_pk_mul_f32 v[12:13], v[12:13], v[0:1] op_sel_hi:[1,0]
	v_pk_mul_f32 v[10:11], v[10:11], v[0:1] op_sel_hi:[1,0]
	v_pk_mul_f32 v[8:9], v[8:9], v[0:1] op_sel_hi:[1,0]
	v_pk_mul_f32 v[6:7], v[6:7], v[0:1] op_sel_hi:[1,0]
	v_pk_mul_f32 v[4:5], v[4:5], v[0:1] op_sel_hi:[1,0]
	v_pk_mul_f32 v[2:3], v[2:3], v[0:1] op_sel_hi:[1,0]
	v_sub_f32_e32 v96, v96, v35
	v_sub_f32_e32 v95, v95, v35
	v_sub_f32_e32 v94, v94, v35
	v_sub_f32_e32 v93, v93, v35
	v_sub_f32_e32 v92, v92, v35
	v_sub_f32_e32 v91, v91, v35
	v_sub_f32_e32 v90, v90, v35
	v_sub_f32_e32 v89, v89, v35
	v_sub_f32_e32 v88, v88, v35
	v_sub_f32_e32 v87, v87, v35
	v_sub_f32_e32 v86, v86, v35
	v_sub_f32_e32 v85, v85, v35
	v_sub_f32_e32 v84, v84, v35
	v_sub_f32_e32 v83, v83, v35
	v_sub_f32_e32 v82, v82, v35
	v_sub_f32_e32 v65, v65, v35
	v_sub_f32_e32 v64, v64, v35
	v_sub_f32_e32 v63, v63, v35
	v_sub_f32_e32 v62, v62, v35
	v_sub_f32_e32 v61, v61, v35
	v_sub_f32_e32 v60, v60, v35
	v_sub_f32_e32 v59, v59, v35
	v_sub_f32_e32 v58, v58, v35
	v_sub_f32_e32 v57, v57, v35
	v_sub_f32_e32 v56, v56, v35
	v_sub_f32_e32 v55, v55, v35
	v_sub_f32_e32 v54, v54, v35
	v_sub_f32_e32 v53, v53, v35
	v_sub_f32_e32 v52, v52, v35
	v_sub_f32_e32 v51, v51, v35
	v_sub_f32_e32 v50, v50, v35
	v_mul_f32_e32 v242, v242, v0
	v_mov_b32_e32 v35, v34
	v_mov_b32_e32 v36, v34
	v_mov_b32_e32 v37, v34
	v_mov_b32_e32 v38, v34
	v_mov_b32_e32 v39, v34
	v_mov_b32_e32 v40, v34
	v_mov_b32_e32 v41, v34
	v_mov_b32_e32 v42, v34
	v_mov_b32_e32 v43, v34
	v_mov_b32_e32 v44, v34
	v_mov_b32_e32 v45, v34
	v_mov_b32_e32 v46, v34
	v_mov_b32_e32 v47, v34
	v_mov_b32_e32 v48, v34
	v_mov_b32_e32 v49, v34
	v_mov_b32_e32 v66, v34
	v_mov_b32_e32 v67, v34
	v_mov_b32_e32 v68, v34
	v_mov_b32_e32 v69, v34
	v_mov_b32_e32 v70, v34
	v_mov_b32_e32 v71, v34
	v_mov_b32_e32 v72, v34
	v_mov_b32_e32 v73, v34
	v_mov_b32_e32 v74, v34
	v_mov_b32_e32 v75, v34
	v_mov_b32_e32 v76, v34
	v_mov_b32_e32 v77, v34
	v_mov_b32_e32 v78, v34
	v_mov_b32_e32 v79, v34
	v_mov_b32_e32 v80, v34
	v_mov_b32_e32 v81, v34
